# v17 + V^T projection epilogue: per (bj,n) block the 12 row-stat loads of tokens 1-3 hoisted next to token 0's, counted waits (16 serialized round trips -> 4 per unit)
# speedup vs baseline: 1.0062x; 1.0062x over previous
; __device__ __forceinline__ u32x2 pack4(f32x4 v) { u32x2 w; w.x = cvt_pk_bf16(v[0], v[1]); w.y = cvt_pk_bf16(v[2], v[3]); return w; }
; __device__ __forceinline__ float rstd_of(const float* ssrow) { const f32x4* q = (const f32x4*)ssrow; const f32x4 a = q[0], b = q[1], c = q[2], d = q[3];
;     const float ss = ((a[0] + a[1]) + (a[2] + a[3])) + ((b[0] + b[1]) + (b[2] + b[3])) + (((c[0] + c[1]) + (c[2] + c[3])) + ((d[0] + d[1]) + (d[2] + d[3])));
;     const float r = __builtin_amdgcn_rsqf(ss * (1.0f / 1024.0f) + 1e-6f); asm volatile("" ::: "memory"); return r; }
;     __device__ __forceinline__ void operator()(const f32x4 (&acc)[2][2][4][2], const Unit& u, int wr, int wc, int fr, int fq) const {
;     ...
;                 const int tok = u.pn * BM + bj * HALF + wc * 32 + n * 16 + fq * 4; f32x4 rs; rs[0] = rstd_of(ss + (size_t)tok * 16); rs[1] = rstd_of(ss + (size_t)tok * 16 + 16); rs[2] = rstd_of(ss + (size_t)tok * 16 + 32); rs[3] = rstd_of(ss + (size_t)tok * 16 + 48);
; #pragma unroll
;                 for (int ai = 0; ai < 2; ++ai)
; #pragma unroll
;                     for (int m = 0; m < 4; ++m) { const int c = u.pm * BM + ai * HALF + wr * 64 + m * 16 + fr; *(u32x2*)(VT + (size_t)c * 32768 + tok) = pack4(acc[ai][bj][m][n] * rs); }
.LBB0_429:
	v_lshl_or_b32 v162, s19, 8, v172
	v_ashrrev_i32_e32 v163, 31, v162
	v_lshlrev_b64 v[128:129], 6, v[162:163]
	v_lshl_add_u64 v[136:137], s[0:1], 0, v[128:129]
	global_load_dwordx4 v[128:131], v[136:137], off offset:16
	global_load_dwordx4 v[132:135], v[136:137], off offset:48
	global_load_dwordx4 v[138:141], v[136:137], off
	global_load_dwordx4 v[166:169], v[136:137], off offset:32
	global_load_dwordx4 v[178:181], v[136:137], off offset:80
	global_load_dwordx4 v[182:185], v[136:137], off offset:112
	global_load_dwordx4 v[186:189], v[136:137], off offset:64
	global_load_dwordx4 v[190:193], v[136:137], off offset:96
	global_load_dwordx4 v[194:197], v[136:137], off offset:144
	global_load_dwordx4 v[216:219], v[136:137], off offset:176
	global_load_dwordx4 v[220:223], v[136:137], off offset:128
	global_load_dwordx4 v[224:227], v[136:137], off offset:160
	global_load_dwordx4 v[228:231], v[136:137], off offset:208
	global_load_dwordx4 v[240:243], v[136:137], off offset:240
	global_load_dwordx4 v[244:247], v[136:137], off offset:192
	global_load_dwordx4 v[248:251], v[136:137], off offset:224
	v_lshl_add_u32 v164, s18, 8, v170
	v_ashrrev_i32_e32 v165, 31, v164
	s_mov_b64 s[18:19], -1
	s_andn2_b64 vcc, exec, s[36:37]
	s_waitcnt vmcnt(12)
	v_mov_b32_e32 v142, v138
	v_mov_b32_e32 v143, v166
	v_mov_b32_e32 v166, v139
	v_pk_add_f32 v[138:139], v[142:143], v[166:167]
	v_mov_b32_e32 v142, v140
	v_mov_b32_e32 v143, v168
	v_mov_b32_e32 v168, v141
	v_pk_add_f32 v[140:141], v[142:143], v[168:169]
	s_nop 0
	v_pk_add_f32 v[138:139], v[138:139], v[140:141]
	v_mov_b32_e32 v140, v128
	v_mov_b32_e32 v141, v132
	v_mov_b32_e32 v132, v129
	v_pk_add_f32 v[128:129], v[140:141], v[132:133]
	v_mov_b32_e32 v132, v130
	v_mov_b32_e32 v133, v134
	v_mov_b32_e32 v134, v131
	v_pk_add_f32 v[130:131], v[132:133], v[134:135]
	s_nop 0
	v_pk_add_f32 v[128:129], v[128:129], v[130:131]
	s_nop 0
	v_pk_add_f32 v[128:129], v[138:139], v[128:129]
	s_nop 0
	v_add_f32_e32 v128, v128, v129
	v_fmamk_f32 v128, v128, 0x3a800000, v201
	v_rsq_f32_e32 v166, v128
	s_nop 1
	s_waitcnt vmcnt(8)
	v_mov_b32_e32 v142, v186
	s_waitcnt vmcnt(8)
	v_mov_b32_e32 v143, v190
	v_mov_b32_e32 v174, v187
	v_mov_b32_e32 v175, v191
	v_pk_add_f32 v[138:139], v[142:143], v[174:175]
	v_mov_b32_e32 v142, v188
	v_mov_b32_e32 v143, v192
	v_mov_b32_e32 v176, v189
	v_mov_b32_e32 v177, v193
	v_pk_add_f32 v[140:141], v[142:143], v[176:177]
	s_nop 0
	v_pk_add_f32 v[138:139], v[138:139], v[140:141]
	v_mov_b32_e32 v140, v178
	v_mov_b32_e32 v141, v182
	v_mov_b32_e32 v132, v179
	v_mov_b32_e32 v133, v183
	v_pk_add_f32 v[128:129], v[140:141], v[132:133]
	v_mov_b32_e32 v132, v180
	v_mov_b32_e32 v133, v184
	v_mov_b32_e32 v134, v181
	v_mov_b32_e32 v135, v185
	v_pk_add_f32 v[130:131], v[132:133], v[134:135]
	s_nop 0
	v_pk_add_f32 v[128:129], v[128:129], v[130:131]
	s_nop 0
	v_pk_add_f32 v[128:129], v[138:139], v[128:129]
	s_nop 0
	v_add_f32_e32 v128, v128, v129
	v_fmamk_f32 v128, v128, 0x3a800000, v201
	v_rsq_f32_e32 v167, v128
	s_nop 1
	v_pk_mul_f32 v[124:125], v[124:125], v[166:167]
	v_pk_mul_f32 v[120:121], v[120:121], v[166:167]
	v_pk_mul_f32 v[116:117], v[116:117], v[166:167]
	v_pk_mul_f32 v[108:109], v[108:109], v[166:167]
	v_pk_mul_f32 v[104:105], v[104:105], v[166:167]
	v_cvt_pk_bf16_f32 v108, v108, v109
	v_cvt_pk_bf16_f32 v104, v104, v105
	v_pk_mul_f32 v[112:113], v[112:113], v[166:167]
	v_pk_mul_f32 v[100:101], v[100:101], v[166:167]
	v_pk_mul_f32 v[96:97], v[96:97], v[166:167]
	v_cvt_pk_bf16_f32 v100, v100, v101
	v_cvt_pk_bf16_f32 v96, v96, v97
	s_waitcnt vmcnt(4)
	v_mov_b32_e32 v142, v220
	s_waitcnt vmcnt(4)
	v_mov_b32_e32 v143, v224
	v_mov_b32_e32 v174, v221
	v_mov_b32_e32 v175, v225
	v_pk_add_f32 v[138:139], v[142:143], v[174:175]
	v_mov_b32_e32 v142, v222
	v_mov_b32_e32 v143, v226
	v_mov_b32_e32 v176, v223
	v_mov_b32_e32 v177, v227
	v_pk_add_f32 v[140:141], v[142:143], v[176:177]
	s_nop 0
	v_pk_add_f32 v[138:139], v[138:139], v[140:141]
	v_mov_b32_e32 v140, v194
	v_mov_b32_e32 v141, v216
	v_mov_b32_e32 v132, v195
	v_mov_b32_e32 v133, v217
	v_pk_add_f32 v[128:129], v[140:141], v[132:133]
	v_mov_b32_e32 v132, v196
	v_mov_b32_e32 v133, v218
	v_mov_b32_e32 v134, v197
	v_mov_b32_e32 v135, v219
	v_pk_add_f32 v[130:131], v[132:133], v[134:135]
	s_nop 0
	v_pk_add_f32 v[128:129], v[128:129], v[130:131]
	s_nop 0
	v_pk_add_f32 v[128:129], v[138:139], v[128:129]
	s_nop 0
	v_add_f32_e32 v128, v128, v129
	v_fmamk_f32 v128, v128, 0x3a800000, v201
	v_rsq_f32_e32 v168, v128
	s_nop 1
	s_waitcnt vmcnt(0)
	v_mov_b32_e32 v174, v244
	s_waitcnt vmcnt(0)
; __device__ __forceinline__ u32x2 pack4(f32x4 v) { u32x2 w; w.x = cvt_pk_bf16(v[0], v[1]); w.y = cvt_pk_bf16(v[2], v[3]); return w; }
;     __device__ __forceinline__ void operator()(const f32x4 (&acc)[2][2][4][2], const Unit& u, int wr, int wc, int fr, int fq) const {
;     ...
;                 const int tok = u.pn * BM + bj * HALF + wc * 32 + n * 16 + fq * 4; f32x4 rs; rs[0] = rstd_of(ss + (size_t)tok * 16); rs[1] = rstd_of(ss + (size_t)tok * 16 + 16); rs[2] = rstd_of(ss + (size_t)tok * 16 + 32); rs[3] = rstd_of(ss + (size_t)tok * 16 + 48);
; #pragma unroll
;                 for (int ai = 0; ai < 2; ++ai)
; #pragma unroll
;                     for (int m = 0; m < 4; ++m) { const int c = u.pm * BM + ai * HALF + wr * 64 + m * 16 + fr; *(u32x2*)(VT + (size_t)c * 32768 + tok) = pack4(acc[ai][bj][m][n] * rs); }
	v_mov_b32_e32 v175, v248
	v_mov_b32_e32 v136, v245
	v_mov_b32_e32 v140, v246
	v_mov_b32_e32 v141, v250
	v_mov_b32_e32 v138, v247
	v_mov_b32_e32 v137, v249
	v_pk_add_f32 v[136:137], v[174:175], v[136:137]
	v_mov_b32_e32 v139, v251
	v_pk_add_f32 v[138:139], v[140:141], v[138:139]
	s_nop 0
	v_pk_add_f32 v[136:137], v[136:137], v[138:139]
	v_mov_b32_e32 v138, v228
	v_mov_b32_e32 v139, v240
	v_mov_b32_e32 v128, v229
	v_mov_b32_e32 v132, v230
	v_mov_b32_e32 v133, v242
	v_mov_b32_e32 v130, v231
	v_mov_b32_e32 v129, v241
	v_pk_add_f32 v[128:129], v[138:139], v[128:129]
	v_mov_b32_e32 v131, v243
	v_pk_add_f32 v[130:131], v[132:133], v[130:131]
	s_nop 0
	v_pk_add_f32 v[128:129], v[128:129], v[130:131]
	v_cvt_pk_bf16_f32 v130, v120, v121
	v_pk_add_f32 v[128:129], v[136:137], v[128:129]
	s_nop 0
	v_add_f32_e32 v128, v128, v129
	v_fmamk_f32 v128, v128, 0x3a800000, v201
	v_rsq_f32_e32 v169, v128
	v_cvt_pk_bf16_f32 v128, v124, v125
	v_lshlrev_b64 v[124:125], 16, v[164:165]
	v_lshl_add_u64 v[124:125], s[20:21], 0, v[124:125]
	v_pk_mul_f32 v[126:127], v[126:127], v[168:169]
	v_pk_mul_f32 v[122:123], v[122:123], v[168:169]
	v_cvt_pk_bf16_f32 v129, v126, v127
	v_lshlrev_b64 v[126:127], 1, v[162:163]
	v_lshl_add_u64 v[124:125], v[124:125], 0, v[126:127]
	global_store_dwordx2 v[124:125], v[128:129], off
	v_or_b32_e32 v128, 16, v164
	v_cvt_pk_bf16_f32 v131, v122, v123
	v_or_b32_e32 v122, 32, v164
	v_ashrrev_i32_e32 v129, 31, v128
	v_ashrrev_i32_e32 v123, 31, v122
	v_pk_mul_f32 v[114:115], v[114:115], v[168:169]
	v_lshlrev_b64 v[120:121], 16, v[128:129]
	v_cvt_pk_bf16_f32 v128, v116, v117
	v_lshlrev_b64 v[116:117], 16, v[122:123]
	v_cvt_pk_bf16_f32 v123, v114, v115
	v_add_u32_e32 v114, 0x80, v164
	v_pk_mul_f32 v[110:111], v[110:111], v[168:169]
	v_ashrrev_i32_e32 v115, 31, v114
	v_cvt_pk_bf16_f32 v109, v110, v111
	v_lshlrev_b64 v[110:111], 16, v[114:115]
	v_lshl_add_u64 v[110:111], s[20:21], 0, v[110:111]
	v_lshl_add_u64 v[114:115], v[110:111], 0, v[126:127]
	global_store_dwordx2 v[114:115], v[108:109], off
	v_add_u32_e32 v108, 0x90, v164
	v_pk_mul_f32 v[118:119], v[118:119], v[168:169]
	v_pk_mul_f32 v[106:107], v[106:107], v[168:169]
	v_ashrrev_i32_e32 v109, 31, v108
	v_cvt_pk_bf16_f32 v129, v118, v119
	v_or_b32_e32 v118, 48, v164
	v_cvt_pk_bf16_f32 v105, v106, v107
	v_lshlrev_b64 v[106:107], 16, v[108:109]
	v_ashrrev_i32_e32 v119, 31, v118
	v_lshl_add_u64 v[106:107], s[20:21], 0, v[106:107]
	v_cvt_pk_bf16_f32 v122, v112, v113
	v_lshlrev_b64 v[112:113], 16, v[118:119]
	v_lshl_add_u64 v[118:119], v[106:107], 0, v[126:127]
	global_store_dwordx2 v[118:119], v[104:105], off
	v_add_u32_e32 v104, 0xa0, v164
	v_pk_mul_f32 v[102:103], v[102:103], v[168:169]
	v_ashrrev_i32_e32 v105, 31, v104
	v_lshl_add_u64 v[112:113], s[20:21], 0, v[112:113]
	v_cvt_pk_bf16_f32 v101, v102, v103
	v_lshlrev_b64 v[102:103], 16, v[104:105]
	v_lshl_add_u64 v[112:113], v[112:113], 0, v[126:127]
	v_lshl_add_u64 v[102:103], s[20:21], 0, v[102:103]
	global_store_dwordx2 v[112:113], v[122:123], off
	v_lshl_add_u64 v[122:123], v[102:103], 0, v[126:127]
	global_store_dwordx2 v[122:123], v[100:101], off
	v_add_u32_e32 v100, 0xb0, v164
	v_pk_mul_f32 v[98:99], v[98:99], v[168:169]
	v_ashrrev_i32_e32 v101, 31, v100
	v_cvt_pk_bf16_f32 v97, v98, v99
	v_lshlrev_b64 v[98:99], 16, v[100:101]
	v_lshl_add_u64 v[120:121], s[20:21], 0, v[120:121]
	v_lshl_add_u64 v[116:117], s[20:21], 0, v[116:117]
	v_lshl_add_u64 v[98:99], s[20:21], 0, v[98:99]
	v_lshl_add_u64 v[120:121], v[120:121], 0, v[126:127]
	v_lshl_add_u64 v[116:117], v[116:117], 0, v[126:127]
	v_lshl_add_u64 v[126:127], v[98:99], 0, v[126:127]
	global_store_dwordx2 v[126:127], v[96:97], off
	v_or_b32_e32 v96, 16, v162
	v_ashrrev_i32_e32 v97, 31, v96
	v_lshlrev_b64 v[96:97], 6, v[96:97]
	global_store_dwordx2 v[120:121], v[130:131], off
	global_store_dwordx2 v[116:117], v[128:129], off
	v_lshl_add_u64 v[104:105], s[0:1], 0, v[96:97]
	global_load_dwordx4 v[96:99], v[104:105], off offset:16
	global_load_dwordx4 v[100:103], v[104:105], off offset:48
	global_load_dwordx4 v[106:109], v[104:105], off
	global_load_dwordx4 v[128:131], v[104:105], off offset:32
	global_load_dwordx4 v[178:181], v[104:105], off offset:80
	global_load_dwordx4 v[182:185], v[104:105], off offset:112
	global_load_dwordx4 v[186:189], v[104:105], off offset:64
	global_load_dwordx4 v[190:193], v[104:105], off offset:96
	global_load_dwordx4 v[194:197], v[104:105], off offset:144
	global_load_dwordx4 v[216:219], v[104:105], off offset:176
	global_load_dwordx4 v[220:223], v[104:105], off offset:128
	global_load_dwordx4 v[224:227], v[104:105], off offset:160
	global_load_dwordx4 v[228:231], v[104:105], off offset:208
	global_load_dwordx4 v[240:243], v[104:105], off offset:240
	global_load_dwordx4 v[244:247], v[104:105], off offset:192
	global_load_dwordx4 v[248:251], v[104:105], off offset:224
	s_waitcnt vmcnt(12)
	v_mov_b32_e32 v110, v106
	s_waitcnt vmcnt(12)
	v_mov_b32_e32 v111, v128
	v_mov_b32_e32 v128, v107
	v_pk_add_f32 v[106:107], v[110:111], v[128:129]
	v_mov_b32_e32 v110, v108
	v_mov_b32_e32 v111, v130
	v_mov_b32_e32 v130, v109
	v_pk_add_f32 v[108:109], v[110:111], v[130:131]
	s_nop 0
	v_pk_add_f32 v[106:107], v[106:107], v[108:109]
	v_mov_b32_e32 v108, v96
	v_mov_b32_e32 v109, v100
	v_mov_b32_e32 v100, v97
	v_pk_add_f32 v[96:97], v[108:109], v[100:101]
	v_mov_b32_e32 v100, v98
	v_mov_b32_e32 v101, v102
	v_mov_b32_e32 v102, v99
	v_pk_add_f32 v[98:99], v[100:101], v[102:103]
	s_nop 0
	v_pk_add_f32 v[96:97], v[96:97], v[98:99]
	s_nop 0
	v_pk_add_f32 v[96:97], v[106:107], v[96:97]
	s_nop 0
	v_add_f32_e32 v96, v96, v97
	v_fmamk_f32 v96, v96, 0x3a800000, v201
	v_rsq_f32_e32 v128, v96
	s_nop 1
	s_waitcnt vmcnt(8)
; __device__ __forceinline__ u32x2 pack4(f32x4 v) { u32x2 w; w.x = cvt_pk_bf16(v[0], v[1]); w.y = cvt_pk_bf16(v[2], v[3]); return w; }
;     __device__ __forceinline__ void operator()(const f32x4 (&acc)[2][2][4][2], const Unit& u, int wr, int wc, int fr, int fq) const {
;     ...
;                 const int tok = u.pn * BM + bj * HALF + wc * 32 + n * 16 + fq * 4; f32x4 rs; rs[0] = rstd_of(ss + (size_t)tok * 16); rs[1] = rstd_of(ss + (size_t)tok * 16 + 16); rs[2] = rstd_of(ss + (size_t)tok * 16 + 32); rs[3] = rstd_of(ss + (size_t)tok * 16 + 48);
; #pragma unroll
;                 for (int ai = 0; ai < 2; ++ai)
; #pragma unroll
;                     for (int m = 0; m < 4; ++m) { const int c = u.pm * BM + ai * HALF + wr * 64 + m * 16 + fr; *(u32x2*)(VT + (size_t)c * 32768 + tok) = pack4(acc[ai][bj][m][n] * rs); }
	v_mov_b32_e32 v110, v186
	s_waitcnt vmcnt(8)
	v_mov_b32_e32 v111, v190
	v_mov_b32_e32 v130, v187
	v_mov_b32_e32 v131, v191
	v_pk_add_f32 v[106:107], v[110:111], v[130:131]
	v_mov_b32_e32 v110, v188
	v_mov_b32_e32 v111, v192
	v_mov_b32_e32 v132, v189
	v_mov_b32_e32 v133, v193
	v_pk_add_f32 v[108:109], v[110:111], v[132:133]
	s_nop 0
	v_pk_add_f32 v[106:107], v[106:107], v[108:109]
	v_mov_b32_e32 v108, v178
	v_mov_b32_e32 v109, v182
	v_mov_b32_e32 v100, v179
	v_mov_b32_e32 v101, v183
	v_pk_add_f32 v[96:97], v[108:109], v[100:101]
	v_mov_b32_e32 v100, v180
	v_mov_b32_e32 v101, v184
	v_mov_b32_e32 v102, v181
	v_mov_b32_e32 v103, v185
	v_pk_add_f32 v[98:99], v[100:101], v[102:103]
	s_nop 0
	v_pk_add_f32 v[96:97], v[96:97], v[98:99]
	s_nop 0
	v_pk_add_f32 v[96:97], v[106:107], v[96:97]
	s_nop 0
	v_add_f32_e32 v96, v96, v97
	v_fmamk_f32 v96, v96, 0x3a800000, v201
	v_rsq_f32_e32 v129, v96
	s_nop 1
	v_pk_mul_f32 v[64:65], v[64:65], v[128:129]
	s_nop 0
	v_cvt_pk_bf16_f32 v64, v64, v65
	v_pk_mul_f32 v[92:93], v[92:93], v[128:129]
	v_pk_mul_f32 v[88:89], v[88:89], v[128:129]
	v_pk_mul_f32 v[84:85], v[84:85], v[128:129]
	v_pk_mul_f32 v[80:81], v[80:81], v[128:129]
	v_pk_mul_f32 v[76:77], v[76:77], v[128:129]
	v_pk_mul_f32 v[72:73], v[72:73], v[128:129]
	v_pk_mul_f32 v[68:69], v[68:69], v[128:129]
	v_cvt_pk_bf16_f32 v92, v92, v93
	v_cvt_pk_bf16_f32 v88, v88, v89
	v_cvt_pk_bf16_f32 v84, v84, v85
	v_cvt_pk_bf16_f32 v80, v80, v81
	v_cvt_pk_bf16_f32 v76, v76, v77
	v_cvt_pk_bf16_f32 v72, v72, v73
	v_cvt_pk_bf16_f32 v68, v68, v69
	s_waitcnt vmcnt(4)
	v_mov_b32_e32 v110, v220
	s_waitcnt vmcnt(4)
	v_mov_b32_e32 v111, v224
	v_mov_b32_e32 v130, v221
	v_mov_b32_e32 v131, v225
	v_pk_add_f32 v[106:107], v[110:111], v[130:131]
	v_mov_b32_e32 v110, v222
	v_mov_b32_e32 v111, v226
	v_mov_b32_e32 v132, v223
	v_mov_b32_e32 v133, v227
	v_pk_add_f32 v[108:109], v[110:111], v[132:133]
	s_nop 0
	v_pk_add_f32 v[106:107], v[106:107], v[108:109]
	v_mov_b32_e32 v108, v194
	v_mov_b32_e32 v109, v216
	v_mov_b32_e32 v100, v195
	v_mov_b32_e32 v101, v217
	v_pk_add_f32 v[96:97], v[108:109], v[100:101]
	v_mov_b32_e32 v100, v196
	v_mov_b32_e32 v101, v218
	v_mov_b32_e32 v102, v197
	v_mov_b32_e32 v103, v219
	v_pk_add_f32 v[98:99], v[100:101], v[102:103]
	s_nop 0
	v_pk_add_f32 v[96:97], v[96:97], v[98:99]
	s_nop 0
	v_pk_add_f32 v[96:97], v[106:107], v[96:97]
	s_nop 0
	v_add_f32_e32 v96, v96, v97
	v_fmamk_f32 v96, v96, 0x3a800000, v201
	v_rsq_f32_e32 v130, v96
	s_nop 1
	s_waitcnt vmcnt(0)
	v_mov_b32_e32 v132, v244
	s_waitcnt vmcnt(0)
	v_mov_b32_e32 v133, v248
	v_mov_b32_e32 v104, v245
	v_mov_b32_e32 v108, v246
	v_mov_b32_e32 v109, v250
	v_mov_b32_e32 v106, v247
	v_mov_b32_e32 v105, v249
	v_pk_add_f32 v[104:105], v[132:133], v[104:105]
	v_mov_b32_e32 v107, v251
	v_pk_add_f32 v[106:107], v[108:109], v[106:107]
	s_nop 0
	v_pk_add_f32 v[104:105], v[104:105], v[106:107]
	v_mov_b32_e32 v106, v228
	v_mov_b32_e32 v107, v240
	v_mov_b32_e32 v96, v229
	v_mov_b32_e32 v100, v230
	v_mov_b32_e32 v101, v242
	v_mov_b32_e32 v98, v231
	v_mov_b32_e32 v97, v241
	v_pk_add_f32 v[96:97], v[106:107], v[96:97]
	v_mov_b32_e32 v99, v243
	v_pk_add_f32 v[98:99], v[100:101], v[98:99]
	s_nop 0
	v_pk_add_f32 v[96:97], v[96:97], v[98:99]
	s_nop 0
	v_pk_add_f32 v[96:97], v[104:105], v[96:97]
	s_nop 0
	v_add_f32_e32 v96, v96, v97
	v_fmamk_f32 v96, v96, 0x3a800000, v201
	v_rsq_f32_e32 v131, v96
	s_nop 0
	v_pk_mul_f32 v[66:67], v[66:67], v[130:131]
	s_nop 0
	v_cvt_pk_bf16_f32 v65, v66, v67
	global_store_dwordx2 v[126:127], v[64:65], off offset:32
	v_or_b32_e32 v64, 0x80, v162
	v_pk_mul_f32 v[94:95], v[94:95], v[130:131]
	v_pk_mul_f32 v[90:91], v[90:91], v[130:131]
	v_pk_mul_f32 v[86:87], v[86:87], v[130:131]
	v_pk_mul_f32 v[82:83], v[82:83], v[130:131]
	v_pk_mul_f32 v[78:79], v[78:79], v[130:131]
	v_pk_mul_f32 v[74:75], v[74:75], v[130:131]
	v_pk_mul_f32 v[70:71], v[70:71], v[130:131]
	v_ashrrev_i32_e32 v65, 31, v64
	v_cvt_pk_bf16_f32 v93, v94, v95
	v_cvt_pk_bf16_f32 v89, v90, v91
	v_cvt_pk_bf16_f32 v85, v86, v87
	v_cvt_pk_bf16_f32 v81, v82, v83
	v_cvt_pk_bf16_f32 v77, v78, v79
	v_cvt_pk_bf16_f32 v73, v74, v75
	v_cvt_pk_bf16_f32 v69, v70, v71
	v_lshlrev_b64 v[64:65], 6, v[64:65]
	global_store_dwordx2 v[124:125], v[92:93], off offset:32
	global_store_dwordx2 v[120:121], v[88:89], off offset:32
	global_store_dwordx2 v[116:117], v[84:85], off offset:32
	global_store_dwordx2 v[112:113], v[80:81], off offset:32
	global_store_dwordx2 v[114:115], v[76:77], off offset:32
	global_store_dwordx2 v[118:119], v[72:73], off offset:32
	global_store_dwordx2 v[122:123], v[68:69], off offset:32
	v_lshl_add_u64 v[72:73], s[0:1], 0, v[64:65]
	global_load_dwordx4 v[64:67], v[72:73], off offset:16
	global_load_dwordx4 v[68:71], v[72:73], off offset:48
	global_load_dwordx4 v[74:77], v[72:73], off
	global_load_dwordx4 v[78:81], v[72:73], off offset:32
	global_load_dwordx4 v[178:181], v[72:73], off offset:80
	global_load_dwordx4 v[182:185], v[72:73], off offset:112
	global_load_dwordx4 v[186:189], v[72:73], off offset:64
	global_load_dwordx4 v[190:193], v[72:73], off offset:96
	global_load_dwordx4 v[194:197], v[72:73], off offset:144
	global_load_dwordx4 v[216:219], v[72:73], off offset:176
	global_load_dwordx4 v[220:223], v[72:73], off offset:128
	global_load_dwordx4 v[224:227], v[72:73], off offset:160
	global_load_dwordx4 v[228:231], v[72:73], off offset:208
	global_load_dwordx4 v[240:243], v[72:73], off offset:240
	global_load_dwordx4 v[244:247], v[72:73], off offset:192
	global_load_dwordx4 v[248:251], v[72:73], off offset:224
	s_waitcnt vmcnt(12)
	v_mov_b32_e32 v82, v74
	s_waitcnt vmcnt(12)
; __device__ __forceinline__ u32x2 pack4(f32x4 v) { u32x2 w; w.x = cvt_pk_bf16(v[0], v[1]); w.y = cvt_pk_bf16(v[2], v[3]); return w; }
;     __device__ __forceinline__ void operator()(const f32x4 (&acc)[2][2][4][2], const Unit& u, int wr, int wc, int fr, int fq) const {
;     ...
;                 const int tok = u.pn * BM + bj * HALF + wc * 32 + n * 16 + fq * 4; f32x4 rs; rs[0] = rstd_of(ss + (size_t)tok * 16); rs[1] = rstd_of(ss + (size_t)tok * 16 + 16); rs[2] = rstd_of(ss + (size_t)tok * 16 + 32); rs[3] = rstd_of(ss + (size_t)tok * 16 + 48);
; #pragma unroll
;                 for (int ai = 0; ai < 2; ++ai)
; #pragma unroll
;                     for (int m = 0; m < 4; ++m) { const int c = u.pm * BM + ai * HALF + wr * 64 + m * 16 + fr; *(u32x2*)(VT + (size_t)c * 32768 + tok) = pack4(acc[ai][bj][m][n] * rs); }
	v_mov_b32_e32 v83, v78
	v_mov_b32_e32 v78, v75
	v_pk_add_f32 v[74:75], v[82:83], v[78:79]
	v_mov_b32_e32 v78, v76
	v_mov_b32_e32 v79, v80
	v_mov_b32_e32 v80, v77
	v_pk_add_f32 v[76:77], v[78:79], v[80:81]
	s_nop 0
	v_pk_add_f32 v[74:75], v[74:75], v[76:77]
	v_mov_b32_e32 v76, v64
	v_mov_b32_e32 v77, v68
	v_mov_b32_e32 v68, v65
	v_pk_add_f32 v[64:65], v[76:77], v[68:69]
	v_mov_b32_e32 v68, v66
	v_mov_b32_e32 v69, v70
	v_mov_b32_e32 v70, v67
	v_pk_add_f32 v[66:67], v[68:69], v[70:71]
	s_nop 0
	v_pk_add_f32 v[64:65], v[64:65], v[66:67]
	s_nop 0
	v_pk_add_f32 v[64:65], v[74:75], v[64:65]
	s_nop 0
	v_add_f32_e32 v64, v64, v65
	v_fmamk_f32 v64, v64, 0x3a800000, v201
	v_rsq_f32_e32 v80, v64
	s_nop 1
	s_waitcnt vmcnt(8)
	v_mov_b32_e32 v78, v186
	s_waitcnt vmcnt(8)
	v_mov_b32_e32 v79, v190
	v_mov_b32_e32 v82, v187
	v_mov_b32_e32 v83, v191
	v_pk_add_f32 v[74:75], v[78:79], v[82:83]
	v_mov_b32_e32 v78, v188
	v_mov_b32_e32 v79, v192
	v_mov_b32_e32 v84, v189
	v_mov_b32_e32 v85, v193
	v_pk_add_f32 v[76:77], v[78:79], v[84:85]
	s_nop 0
	v_pk_add_f32 v[74:75], v[74:75], v[76:77]
	v_mov_b32_e32 v76, v178
	v_mov_b32_e32 v77, v182
	v_mov_b32_e32 v68, v179
	v_mov_b32_e32 v69, v183
	v_pk_add_f32 v[64:65], v[76:77], v[68:69]
	v_mov_b32_e32 v68, v180
	v_mov_b32_e32 v69, v184
	v_mov_b32_e32 v70, v181
	v_mov_b32_e32 v71, v185
	v_pk_add_f32 v[66:67], v[68:69], v[70:71]
	s_nop 0
	v_pk_add_f32 v[64:65], v[64:65], v[66:67]
	s_nop 0
	v_pk_add_f32 v[64:65], v[74:75], v[64:65]
	s_nop 0
	v_add_f32_e32 v64, v64, v65
	v_fmamk_f32 v64, v64, 0x3a800000, v201
	v_rsq_f32_e32 v81, v64
	s_nop 1
	v_pk_mul_f32 v[32:33], v[32:33], v[80:81]
	s_nop 0
	v_cvt_pk_bf16_f32 v32, v32, v33
	v_pk_mul_f32 v[60:61], v[60:61], v[80:81]
	v_pk_mul_f32 v[56:57], v[56:57], v[80:81]
	v_pk_mul_f32 v[52:53], v[52:53], v[80:81]
	v_pk_mul_f32 v[48:49], v[48:49], v[80:81]
	v_pk_mul_f32 v[44:45], v[44:45], v[80:81]
	v_pk_mul_f32 v[40:41], v[40:41], v[80:81]
	v_pk_mul_f32 v[36:37], v[36:37], v[80:81]
	v_cvt_pk_bf16_f32 v60, v60, v61
	v_cvt_pk_bf16_f32 v56, v56, v57
	v_cvt_pk_bf16_f32 v52, v52, v53
	v_cvt_pk_bf16_f32 v48, v48, v49
	v_cvt_pk_bf16_f32 v44, v44, v45
	v_cvt_pk_bf16_f32 v40, v40, v41
	v_cvt_pk_bf16_f32 v36, v36, v37
	s_waitcnt vmcnt(4)
	v_mov_b32_e32 v78, v220
	s_waitcnt vmcnt(4)
	v_mov_b32_e32 v79, v224
	v_mov_b32_e32 v82, v221
	v_mov_b32_e32 v83, v225
	v_pk_add_f32 v[74:75], v[78:79], v[82:83]
	v_mov_b32_e32 v78, v222
	v_mov_b32_e32 v79, v226
	v_mov_b32_e32 v84, v223
	v_mov_b32_e32 v85, v227
	v_pk_add_f32 v[76:77], v[78:79], v[84:85]
	s_nop 0
	v_pk_add_f32 v[74:75], v[74:75], v[76:77]
	v_mov_b32_e32 v76, v194
	v_mov_b32_e32 v77, v216
	v_mov_b32_e32 v68, v195
	v_mov_b32_e32 v69, v217
	v_pk_add_f32 v[64:65], v[76:77], v[68:69]
	v_mov_b32_e32 v68, v196
	v_mov_b32_e32 v69, v218
	v_mov_b32_e32 v70, v197
	v_mov_b32_e32 v71, v219
	v_pk_add_f32 v[66:67], v[68:69], v[70:71]
	s_nop 0
	v_pk_add_f32 v[64:65], v[64:65], v[66:67]
	s_nop 0
	v_pk_add_f32 v[64:65], v[74:75], v[64:65]
	s_nop 0
	v_add_f32_e32 v64, v64, v65
	v_fmamk_f32 v64, v64, 0x3a800000, v201
	v_rsq_f32_e32 v82, v64
	s_nop 1
	s_waitcnt vmcnt(0)
	v_mov_b32_e32 v84, v244
	s_waitcnt vmcnt(0)
	v_mov_b32_e32 v85, v248
	v_mov_b32_e32 v72, v245
	v_mov_b32_e32 v76, v246
	v_mov_b32_e32 v77, v250
	v_mov_b32_e32 v74, v247
	v_mov_b32_e32 v73, v249
	v_pk_add_f32 v[72:73], v[84:85], v[72:73]
	v_mov_b32_e32 v75, v251
	v_pk_add_f32 v[74:75], v[76:77], v[74:75]
	s_nop 0
	v_pk_add_f32 v[72:73], v[72:73], v[74:75]
	v_mov_b32_e32 v74, v228
	v_mov_b32_e32 v75, v240
	v_mov_b32_e32 v64, v229
	v_mov_b32_e32 v68, v230
	v_mov_b32_e32 v69, v242
	v_mov_b32_e32 v66, v231
	v_mov_b32_e32 v65, v241
	v_pk_add_f32 v[64:65], v[74:75], v[64:65]
	v_mov_b32_e32 v67, v243
	v_pk_add_f32 v[66:67], v[68:69], v[66:67]
	s_nop 0
	v_pk_add_f32 v[64:65], v[64:65], v[66:67]
	s_nop 0
	v_pk_add_f32 v[64:65], v[72:73], v[64:65]
	s_nop 0
	v_add_f32_e32 v64, v64, v65
	v_fmamk_f32 v64, v64, 0x3a800000, v201
	v_rsq_f32_e32 v83, v64
	s_nop 0
	v_pk_mul_f32 v[34:35], v[34:35], v[82:83]
	s_nop 0
	v_cvt_pk_bf16_f32 v33, v34, v35
	global_store_dwordx2 v[126:127], v[32:33], off offset:256
	v_or_b32_e32 v32, 0x90, v162
	v_pk_mul_f32 v[62:63], v[62:63], v[82:83]
	v_pk_mul_f32 v[58:59], v[58:59], v[82:83]
	v_pk_mul_f32 v[54:55], v[54:55], v[82:83]
	v_pk_mul_f32 v[50:51], v[50:51], v[82:83]
	v_pk_mul_f32 v[46:47], v[46:47], v[82:83]
	v_pk_mul_f32 v[42:43], v[42:43], v[82:83]
	v_pk_mul_f32 v[38:39], v[38:39], v[82:83]
	v_ashrrev_i32_e32 v33, 31, v32
	v_cvt_pk_bf16_f32 v61, v62, v63
	v_cvt_pk_bf16_f32 v57, v58, v59
	v_cvt_pk_bf16_f32 v53, v54, v55
	v_cvt_pk_bf16_f32 v49, v50, v51
	v_cvt_pk_bf16_f32 v45, v46, v47
	v_cvt_pk_bf16_f32 v41, v42, v43
	v_cvt_pk_bf16_f32 v37, v38, v39
	v_lshlrev_b64 v[32:33], 6, v[32:33]
	global_store_dwordx2 v[124:125], v[60:61], off offset:256
	global_store_dwordx2 v[120:121], v[56:57], off offset:256
	global_store_dwordx2 v[116:117], v[52:53], off offset:256
	global_store_dwordx2 v[112:113], v[48:49], off offset:256
	global_store_dwordx2 v[114:115], v[44:45], off offset:256
	global_store_dwordx2 v[118:119], v[40:41], off offset:256
	global_store_dwordx2 v[122:123], v[36:37], off offset:256
	v_lshl_add_u64 v[40:41], s[0:1], 0, v[32:33]
	global_load_dwordx4 v[32:35], v[40:41], off offset:16
	global_load_dwordx4 v[36:39], v[40:41], off offset:48
	global_load_dwordx4 v[42:45], v[40:41], off
	global_load_dwordx4 v[46:49], v[40:41], off offset:32
	global_load_dwordx4 v[178:181], v[40:41], off offset:80
	global_load_dwordx4 v[182:185], v[40:41], off offset:112
	global_load_dwordx4 v[186:189], v[40:41], off offset:64
	global_load_dwordx4 v[190:193], v[40:41], off offset:96
	global_load_dwordx4 v[194:197], v[40:41], off offset:144
	global_load_dwordx4 v[216:219], v[40:41], off offset:176
	global_load_dwordx4 v[220:223], v[40:41], off offset:128
	global_load_dwordx4 v[224:227], v[40:41], off offset:160
	global_load_dwordx4 v[228:231], v[40:41], off offset:208
	global_load_dwordx4 v[240:243], v[40:41], off offset:240
	global_load_dwordx4 v[244:247], v[40:41], off offset:192
	global_load_dwordx4 v[248:251], v[40:41], off offset:224
	s_waitcnt vmcnt(12)
;     __device__ __forceinline__ void operator()(const f32x4 (&acc)[2][2][4][2], const Unit& u, int wr, int wc, int fr, int fq) const {
;     ...
;                 const int tok = u.pn * BM + bj * HALF + wc * 32 + n * 16 + fq * 4; f32x4 rs; rs[0] = rstd_of(ss + (size_t)tok * 16); rs[1] = rstd_of(ss + (size_t)tok * 16 + 16); rs[2] = rstd_of(ss + (size_t)tok * 16 + 32); rs[3] = rstd_of(ss + (size_t)tok * 16 + 48);
; #pragma unroll
;                 for (int ai = 0; ai < 2; ++ai)
; #pragma unroll
;                     for (int m = 0; m < 4; ++m) { const int c = u.pm * BM + ai * HALF + wr * 64 + m * 16 + fr; *(u32x2*)(VT + (size_t)c * 32768 + tok) = pack4(acc[ai][bj][m][n] * rs); }
; template <class Epi, class Sched>
; __device__ __forceinline__ void gemm_simple(const Gemm g, const Sched& S, const Epi& E) {
;     ...
;     for (int ui = 0; S.next(ui, u); ++ui) {
;         f32x4 acc[2][2][4][2];
; #pragma unroll
;         for (int a = 0; a < 2; ++a)
; #pragma unroll
;             for (int b = 0; b < 2; ++b)
; #pragma unroll
;                 for (int m = 0; m < 4; ++m)
; #pragma unroll
;                     for (int n = 0; n < 2; ++n) acc[a][b][m][n] = (f32x4){0.f, 0.f, 0.f, 0.f};
;         const bf16_t* Ab = g.A + (size_t)(u.pm * BM + wr * 64 + fr) * K + fq * 8;
;         const bf16_t* Bb = g.Bt + (size_t)(u.pn * BM + wc * 32 + fr) * K + fq * 8;
;         for (int k0 = 0; k0 < K; k0 += 32) {
;             bf16x8 af[2][4], bfr[2][2];
; #pragma unroll
;             for (int ai = 0; ai < 2; ++ai)
; #pragma unroll
;                 for (int m = 0; m < 4; ++m) af[ai][m] = *(const bf16x8*)(Ab + (size_t)(ai * HALF + m * 16) * K + k0);
; #pragma unroll
;             for (int bj = 0; bj < 2; ++bj)
; #pragma unroll
;                 for (int n = 0; n < 2; ++n) bfr[bj][n] = *(const bf16x8*)(Bb + (size_t)(bj * HALF + n * 16) * K + k0);
; #pragma unroll
;             for (int ai = 0; ai < 2; ++ai)
; #pragma unroll
;                 for (int bj = 0; bj < 2; ++bj)
; #pragma unroll
;                     for (int m = 0; m < 4; ++m)
; #pragma unroll
;                         for (int n = 0; n < 2; ++n) acc[ai][bj][m][n] = __builtin_amdgcn_mfma_f32_16x16x32_bf16(bfr[bj][n], af[ai][m], acc[ai][bj][m][n], 0, 0, 0);
;         }
;         E(acc, u, wr, wc, fr, fq);
;     }
	v_mov_b32_e32 v50, v42
	s_waitcnt vmcnt(12)
	v_mov_b32_e32 v51, v46
	v_mov_b32_e32 v46, v43
	v_pk_add_f32 v[42:43], v[50:51], v[46:47]
	v_mov_b32_e32 v46, v44
	v_mov_b32_e32 v47, v48
	v_mov_b32_e32 v48, v45
	v_pk_add_f32 v[44:45], v[46:47], v[48:49]
	s_nop 0
	v_pk_add_f32 v[42:43], v[42:43], v[44:45]
	v_mov_b32_e32 v44, v32
	v_mov_b32_e32 v45, v36
	v_mov_b32_e32 v36, v33
	v_pk_add_f32 v[32:33], v[44:45], v[36:37]
	v_mov_b32_e32 v36, v34
	v_mov_b32_e32 v37, v38
	v_mov_b32_e32 v38, v35
	v_pk_add_f32 v[34:35], v[36:37], v[38:39]
	s_nop 0
	v_pk_add_f32 v[32:33], v[32:33], v[34:35]
	s_nop 0
	v_pk_add_f32 v[32:33], v[42:43], v[32:33]
	s_nop 0
	v_add_f32_e32 v32, v32, v33
	v_fmamk_f32 v32, v32, 0x3a800000, v201
	v_rsq_f32_e32 v48, v32
	s_nop 1
	s_waitcnt vmcnt(8)
	v_mov_b32_e32 v46, v186
	s_waitcnt vmcnt(8)
	v_mov_b32_e32 v47, v190
	v_mov_b32_e32 v50, v187
	v_mov_b32_e32 v51, v191
	v_pk_add_f32 v[42:43], v[46:47], v[50:51]
	v_mov_b32_e32 v46, v188
	v_mov_b32_e32 v47, v192
	v_mov_b32_e32 v52, v189
	v_mov_b32_e32 v53, v193
	v_pk_add_f32 v[44:45], v[46:47], v[52:53]
	s_nop 0
	v_pk_add_f32 v[42:43], v[42:43], v[44:45]
	v_mov_b32_e32 v44, v178
	v_mov_b32_e32 v45, v182
	v_mov_b32_e32 v36, v179
	v_mov_b32_e32 v37, v183
	v_pk_add_f32 v[32:33], v[44:45], v[36:37]
	v_mov_b32_e32 v36, v180
	v_mov_b32_e32 v37, v184
	v_mov_b32_e32 v38, v181
	v_mov_b32_e32 v39, v185
	v_pk_add_f32 v[34:35], v[36:37], v[38:39]
	s_nop 0
	v_pk_add_f32 v[32:33], v[32:33], v[34:35]
	s_nop 0
	v_pk_add_f32 v[32:33], v[42:43], v[32:33]
	s_nop 0
	v_add_f32_e32 v32, v32, v33
	v_fmamk_f32 v32, v32, 0x3a800000, v201
	v_rsq_f32_e32 v49, v32
	s_nop 1
	v_pk_mul_f32 v[28:29], v[28:29], v[48:49]
	v_pk_mul_f32 v[24:25], v[24:25], v[48:49]
	v_pk_mul_f32 v[20:21], v[20:21], v[48:49]
	v_pk_mul_f32 v[16:17], v[16:17], v[48:49]
	v_pk_mul_f32 v[12:13], v[12:13], v[48:49]
	v_pk_mul_f32 v[8:9], v[8:9], v[48:49]
	v_pk_mul_f32 v[4:5], v[4:5], v[48:49]
	v_pk_mul_f32 v[0:1], v[0:1], v[48:49]
	v_cvt_pk_bf16_f32 v28, v28, v29
	v_cvt_pk_bf16_f32 v24, v24, v25
	v_cvt_pk_bf16_f32 v20, v20, v21
	v_cvt_pk_bf16_f32 v16, v16, v17
	v_cvt_pk_bf16_f32 v12, v12, v13
	v_cvt_pk_bf16_f32 v8, v8, v9
	v_cvt_pk_bf16_f32 v4, v4, v5
	v_cvt_pk_bf16_f32 v0, v0, v1
	s_waitcnt vmcnt(4)
	v_mov_b32_e32 v46, v220
	s_waitcnt vmcnt(4)
	v_mov_b32_e32 v47, v224
	v_mov_b32_e32 v50, v221
	v_mov_b32_e32 v51, v225
	v_pk_add_f32 v[42:43], v[46:47], v[50:51]
	v_mov_b32_e32 v46, v222
	v_mov_b32_e32 v47, v226
	v_mov_b32_e32 v52, v223
	v_mov_b32_e32 v53, v227
	v_pk_add_f32 v[44:45], v[46:47], v[52:53]
	s_nop 0
	v_pk_add_f32 v[42:43], v[42:43], v[44:45]
	v_mov_b32_e32 v44, v194
	v_mov_b32_e32 v45, v216
	v_mov_b32_e32 v36, v195
	v_mov_b32_e32 v37, v217
	v_pk_add_f32 v[32:33], v[44:45], v[36:37]
	v_mov_b32_e32 v36, v196
	v_mov_b32_e32 v37, v218
	v_mov_b32_e32 v38, v197
	v_mov_b32_e32 v39, v219
	v_pk_add_f32 v[34:35], v[36:37], v[38:39]
	s_nop 0
	v_pk_add_f32 v[32:33], v[32:33], v[34:35]
	s_nop 0
	v_pk_add_f32 v[32:33], v[42:43], v[32:33]
	s_nop 0
	v_add_f32_e32 v32, v32, v33
	v_fmamk_f32 v32, v32, 0x3a800000, v201
	v_rsq_f32_e32 v50, v32
	s_nop 1
	s_waitcnt vmcnt(0)
	v_mov_b32_e32 v52, v244
	s_waitcnt vmcnt(0)
	v_mov_b32_e32 v53, v248
	v_mov_b32_e32 v40, v245
	v_mov_b32_e32 v44, v246
	v_mov_b32_e32 v45, v250
	v_mov_b32_e32 v42, v247
	v_mov_b32_e32 v41, v249
	v_pk_add_f32 v[40:41], v[52:53], v[40:41]
	v_mov_b32_e32 v43, v251
	v_pk_add_f32 v[42:43], v[44:45], v[42:43]
	s_nop 0
	v_pk_add_f32 v[40:41], v[40:41], v[42:43]
	v_mov_b32_e32 v42, v228
	v_mov_b32_e32 v43, v240
	v_mov_b32_e32 v32, v229
	v_mov_b32_e32 v36, v230
	v_mov_b32_e32 v37, v242
	v_mov_b32_e32 v34, v231
	v_mov_b32_e32 v33, v241
	v_pk_add_f32 v[32:33], v[42:43], v[32:33]
	v_mov_b32_e32 v35, v243
	v_pk_add_f32 v[34:35], v[36:37], v[34:35]
	s_nop 0
	v_pk_add_f32 v[32:33], v[32:33], v[34:35]
	s_nop 0
	v_pk_add_f32 v[32:33], v[40:41], v[32:33]
	s_nop 0
	v_add_f32_e32 v32, v32, v33
	v_fmamk_f32 v32, v32, 0x3a800000, v201
	v_rsq_f32_e32 v51, v32
	s_nop 0
	v_pk_mul_f32 v[30:31], v[30:31], v[50:51]
	v_pk_mul_f32 v[26:27], v[26:27], v[50:51]
	v_pk_mul_f32 v[22:23], v[22:23], v[50:51]
	v_pk_mul_f32 v[18:19], v[18:19], v[50:51]
	v_pk_mul_f32 v[14:15], v[14:15], v[50:51]
	v_pk_mul_f32 v[10:11], v[10:11], v[50:51]
	v_pk_mul_f32 v[6:7], v[6:7], v[50:51]
	v_pk_mul_f32 v[2:3], v[2:3], v[50:51]
	v_cvt_pk_bf16_f32 v29, v30, v31
	v_cvt_pk_bf16_f32 v25, v26, v27
	v_cvt_pk_bf16_f32 v21, v22, v23
	v_cvt_pk_bf16_f32 v17, v18, v19
	v_cvt_pk_bf16_f32 v13, v14, v15
	v_cvt_pk_bf16_f32 v9, v10, v11
	v_cvt_pk_bf16_f32 v5, v6, v7
	v_cvt_pk_bf16_f32 v1, v2, v3
	global_store_dwordx2 v[124:125], v[28:29], off offset:288
	global_store_dwordx2 v[120:121], v[24:25], off offset:288
	global_store_dwordx2 v[116:117], v[20:21], off offset:288
	global_store_dwordx2 v[112:113], v[16:17], off offset:288
	global_store_dwordx2 v[114:115], v[12:13], off offset:288
	global_store_dwordx2 v[118:119], v[8:9], off offset:288
	global_store_dwordx2 v[122:123], v[4:5], off offset:288
	global_store_dwordx2 v[126:127], v[0:1], off offset:288
	s_cbranch_vccnz .LBB0_418
	s_andn2_b64 vcc, exec, s[6:7]
	s_cbranch_vccnz .LBB0_417
	s_barrier
	s_branch .LBB0_417
